# hoisted gain loads in first rmsnorm (rms_rows_bf16)
# speedup vs baseline: 1.0090x; 1.0028x over previous
; DI void rms_rows_bf16(const Ctx& C, const float* x, const float* g, bf16* out) {
;     for (int m = C.gw; m < T; m += C.ngw) {
;         const f32x4* xr = (const f32x4*)(x + (size_t)m * D) + C.lane; f32x4 v[8]; float s = 0.f;
; #pragma unroll
;         for (int j = 0; j < 8; ++j) { v[j] = xr[64 * j]; s += (v[j].x * v[j].x + v[j].y * v[j].y) + (v[j].z * v[j].z + v[j].w * v[j].w); }
;         const float rstd = 1.0f / sqrtf(wave_sum(s) * (1.0f / D) + EPS);
.LBB0_48:
	v_add_co_u32_e32 v18, vcc, 0xfffff000, v52
	global_load_dwordx4 v[10:13], v[52:53], off offset:-3072
	global_load_dwordx4 v[14:17], v[52:53], off offset:-2048
	global_load_dwordx4 v[6:9], v[52:53], off
	v_addc_co_u32_e32 v19, vcc, -1, v53, vcc
	global_load_dwordx4 v[34:37], v[18:19], off offset:-3072
	global_load_dwordx4 v[30:33], v[18:19], off offset:-2048
	global_load_dwordx4 v[26:29], v[18:19], off offset:-1024
	global_load_dwordx4 v[22:25], v[52:53], off offset:-4096
	s_nop 0
	global_load_dwordx4 v[18:21], v[52:53], off offset:-1024
	global_load_dwordx4 v[38:41], v[0:1], off
	s_add_i32 s8, s8, s16
	s_cmpk_lt_i32 s8, 0x4000
	v_lshl_add_u64 v[52:53], v[52:53], 0, s[20:21]
	s_waitcnt vmcnt(0)
	v_mov_b32_e32 v70, v35
	v_pk_mul_f32 v[60:61], v[16:17], v[16:17]
	v_pk_mul_f32 v[62:63], v[14:15], v[14:15]
	v_mul_f32_e32 v81, v8, v8
	v_mul_f32_e32 v2, v19, v19
	v_mul_f32_e32 v64, v21, v21
	v_mul_f32_e32 v87, v9, v9
	v_pk_mov_b32 v[66:67], v[62:63], v[60:61] op_sel:[1,0]
	v_mov_b32_e32 v63, v61
	v_pk_fma_f32 v[60:61], v[18:19], v[18:19], v[2:3] op_sel_hi:[1,1,0]
	v_pk_fma_f32 v[64:65], v[20:21], v[20:21], v[64:65] op_sel_hi:[1,1,0]
	v_mov_b32_e32 v71, v31
	v_mov_b32_e32 v74, v37
	v_mov_b32_e32 v75, v33
	v_mov_b32_e32 v68, v34
	v_mov_b32_e32 v69, v30
	v_mov_b32_e32 v72, v36
	v_mov_b32_e32 v73, v32
	v_pk_mul_f32 v[76:77], v[28:29], v[28:29]
	v_pk_mul_f32 v[78:79], v[26:27], v[26:27]
	v_pk_add_f32 v[62:63], v[66:67], v[62:63]
	v_mov_b32_e32 v61, v81
	v_mov_b32_e32 v65, v87
	v_pk_mul_f32 v[66:67], v[70:71], v[70:71]
	v_pk_mul_f32 v[70:71], v[74:75], v[74:75]
	v_pk_mov_b32 v[74:75], v[78:79], v[76:77] op_sel:[1,0]
	v_mov_b32_e32 v79, v77
	v_pk_add_f32 v[60:61], v[60:61], v[64:65]
	v_pk_fma_f32 v[64:65], v[68:69], v[68:69], v[66:67]
	v_pk_fma_f32 v[66:67], v[72:73], v[72:73], v[70:71]
	v_mul_f32_e32 v2, v23, v23
	v_mul_f32_e32 v80, v25, v25
	v_pk_add_f32 v[68:69], v[74:75], v[78:79]
	v_pk_add_f32 v[64:65], v[64:65], v[66:67]
	v_mul_f32_e32 v59, v10, v10
	v_mul_f32_e32 v82, v11, v11
	v_mul_f32_e32 v83, v12, v12
	v_mul_f32_e32 v84, v13, v13
	v_pk_fma_f32 v[76:77], v[22:23], v[22:23], v[2:3] op_sel_hi:[1,1,0]
	v_pk_fma_f32 v[80:81], v[24:25], v[24:25], v[80:81] op_sel_hi:[1,1,0]
	v_pk_add_f32 v[66:67], v[68:69], v[68:69] op_sel:[0,1] op_sel_hi:[1,0]
	v_pk_add_f32 v[64:65], v[64:65], v[64:65] op_sel:[0,1] op_sel_hi:[1,0]
	v_mov_b32_e32 v77, v83
	v_mov_b32_e32 v81, v84
	v_mov_b32_e32 v67, v82
	v_mov_b32_e32 v65, v59
	v_pk_add_f32 v[68:69], v[76:77], v[80:81]
	v_pk_add_f32 v[64:65], v[64:65], v[66:67]
	v_mul_f32_e32 v85, v6, v6
	v_pk_add_f32 v[64:65], v[64:65], v[68:69]
	v_mul_f32_e32 v86, v7, v7
	v_pk_add_f32 v[62:63], v[62:63], v[62:63] op_sel:[0,1] op_sel_hi:[1,0]
	v_pk_add_f32 v[64:65], v[64:65], v[64:65] op_sel:[0,1] op_sel_hi:[1,0]
	v_mov_b32_e32 v63, v86
	v_mov_b32_e32 v65, v85
	v_pk_add_f32 v[62:63], v[64:65], v[62:63]
	s_nop 0
	v_pk_add_f32 v[60:61], v[62:63], v[60:61]
	s_nop 0
	v_add_f32_e32 v2, v60, v61
	ds_bpermute_b32 v59, v5, v2
	s_waitcnt lgkmcnt(0)
	v_add_f32_e32 v2, v2, v59
	ds_bpermute_b32 v59, v54, v2
	s_waitcnt lgkmcnt(0)
	v_add_f32_e32 v2, v2, v59
	ds_bpermute_b32 v59, v55, v2
	s_waitcnt lgkmcnt(0)
	v_add_f32_e32 v2, v2, v59
	ds_bpermute_b32 v59, v56, v2
	s_waitcnt lgkmcnt(0)
	v_add_f32_e32 v2, v2, v59
	ds_bpermute_b32 v59, v57, v2
	s_waitcnt lgkmcnt(0)
	v_add_f32_e32 v2, v2, v59
	ds_bpermute_b32 v59, v58, v2
	s_waitcnt lgkmcnt(0)
; DI unsigned pk2(float lo, float hi) { return pg8::cvt_pk_bf16(lo, hi); }
; DI void rms_rows_bf16(const Ctx& C, const float* x, const float* g, bf16* out) {
;     ...
;         const float rstd = 1.0f / sqrtf(wave_sum(s) * (1.0f / D) + EPS);
;         const f32x4* gr = (const f32x4*)g + C.lane; v2u* o = (v2u*)(out + (size_t)m * D) + C.lane;
; #pragma unroll
;         for (int j = 0; j < 8; ++j) { const f32x4 gv = gr[64 * j]; v2u w; w.x = pk2(v[j].x * rstd * gv.x, v[j].y * rstd * gv.y); w.y = pk2(v[j].z * rstd * gv.z, v[j].w * rstd * gv.w); o[64 * j] = w; }
	v_add_f32_e32 v2, v2, v59
	v_fmamk_f32 v2, v2, 0x3a000000, v209
	v_mul_f32_e32 v59, 0x4f800000, v2
	v_cmp_gt_f32_e32 vcc, s89, v2
	s_nop 1
	v_cndmask_b32_e32 v2, v2, v59, vcc
	v_sqrt_f32_e32 v59, v2
	s_nop 0
	v_add_u32_e32 v60, -1, v59
	v_add_u32_e32 v61, 1, v59
	v_fma_f32 v62, -v60, v59, v2
	v_fma_f32 v63, -v61, v59, v2
	v_cmp_ge_f32_e64 s[0:1], 0, v62
	s_nop 1
	v_cndmask_b32_e64 v59, v59, v60, s[0:1]
	v_cmp_lt_f32_e64 s[0:1], 0, v63
	s_nop 1
	v_cndmask_b32_e64 v59, v59, v61, s[0:1]
	v_mul_f32_e32 v60, 0x37800000, v59
	v_cndmask_b32_e32 v59, v59, v60, vcc
	v_cmp_class_f32_e32 vcc, v2, v210
	s_nop 1
	v_cndmask_b32_e32 v2, v59, v2, vcc
	v_div_scale_f32 v59, s[0:1], v2, v2, 1.0
	v_rcp_f32_e32 v61, v59
	v_div_scale_f32 v60, vcc, 1.0, v2, 1.0
	v_fma_f32 v62, -v59, v61, 1.0
	v_fmac_f32_e32 v61, v62, v61
	v_mul_f32_e32 v62, v60, v61
	v_fma_f32 v63, -v59, v62, v60
	v_fmac_f32_e32 v62, v63, v61
	v_fma_f32 v59, -v59, v62, v60
	v_div_fmas_f32 v59, v59, v61, v62
	v_div_fixup_f32 v2, v59, v2, 1.0
	v_pk_mul_f32 v[34:35], v[34:35], v[2:3] op_sel_hi:[1,0]
	v_pk_mul_f32 v[36:37], v[36:37], v[2:3] op_sel_hi:[1,0]
	v_pk_mul_f32 v[34:35], v[38:39], v[34:35]
	v_pk_mul_f32 v[36:37], v[40:41], v[36:37]
	v_cvt_pk_bf16_f32 v34, v34, v35
	v_cvt_pk_bf16_f32 v35, v36, v37
	global_load_dwordx4 v[100:103], v[0:1], off offset:1024
	global_load_dwordx4 v[104:107], v[0:1], off offset:2048
	global_load_dwordx4 v[108:111], v[0:1], off offset:3072
	global_load_dwordx4 v[112:115], v[42:43], off
	global_load_dwordx4 v[116:119], v[44:45], off
	global_load_dwordx4 v[120:123], v[46:47], off
	global_load_dwordx4 v[124:127], v[48:49], off
	global_store_dwordx2 v[50:51], v[34:35], off
	v_pk_mul_f32 v[30:31], v[30:31], v[2:3] op_sel_hi:[1,0]
	v_pk_mul_f32 v[32:33], v[32:33], v[2:3] op_sel_hi:[1,0]
	v_pk_mul_f32 v[26:27], v[26:27], v[2:3] op_sel_hi:[1,0]
	v_pk_mul_f32 v[28:29], v[28:29], v[2:3] op_sel_hi:[1,0]
	v_pk_mul_f32 v[22:23], v[22:23], v[2:3] op_sel_hi:[1,0]
	v_pk_mul_f32 v[24:25], v[24:25], v[2:3] op_sel_hi:[1,0]
	v_pk_mul_f32 v[10:11], v[10:11], v[2:3] op_sel_hi:[1,0]
	v_pk_mul_f32 v[12:13], v[12:13], v[2:3] op_sel_hi:[1,0]
	v_pk_mul_f32 v[14:15], v[14:15], v[2:3] op_sel_hi:[1,0]
	v_pk_mul_f32 v[16:17], v[16:17], v[2:3] op_sel_hi:[1,0]
	v_pk_mul_f32 v[6:7], v[6:7], v[2:3] op_sel_hi:[1,0]
	v_pk_mul_f32 v[8:9], v[8:9], v[2:3] op_sel_hi:[1,0]
	s_waitcnt vmcnt(7)
	v_pk_mul_f32 v[30:31], v[100:101], v[30:31]
	v_pk_mul_f32 v[32:33], v[102:103], v[32:33]
	v_cvt_pk_bf16_f32 v30, v30, v31
	v_cvt_pk_bf16_f32 v31, v32, v33
	global_store_dwordx2 v[50:51], v[30:31], off offset:512
	s_waitcnt vmcnt(7)
	v_pk_mul_f32 v[26:27], v[104:105], v[26:27]
	v_pk_mul_f32 v[28:29], v[106:107], v[28:29]
	v_cvt_pk_bf16_f32 v26, v26, v27
	v_cvt_pk_bf16_f32 v27, v28, v29
	global_store_dwordx2 v[50:51], v[26:27], off offset:1024
	s_waitcnt vmcnt(7)
	v_pk_mul_f32 v[22:23], v[108:109], v[22:23]
	v_pk_mul_f32 v[24:25], v[110:111], v[24:25]
	v_cvt_pk_bf16_f32 v22, v22, v23
	v_cvt_pk_bf16_f32 v23, v24, v25
	global_store_dwordx2 v[50:51], v[22:23], off offset:1536
	s_waitcnt vmcnt(7)
	v_pk_mul_f32 v[10:11], v[10:11], v[112:113]
	v_pk_mul_f32 v[12:13], v[12:13], v[114:115]
	v_cvt_pk_bf16_f32 v10, v10, v11
	v_cvt_pk_bf16_f32 v11, v12, v13
	global_store_dwordx2 v[50:51], v[10:11], off offset:2048
	s_waitcnt vmcnt(7)
	v_pk_mul_f32 v[10:11], v[14:15], v[116:117]
	v_pk_mul_f32 v[12:13], v[16:17], v[118:119]
	v_cvt_pk_bf16_f32 v10, v10, v11
	v_cvt_pk_bf16_f32 v11, v12, v13
	global_store_dwordx2 v[50:51], v[10:11], off offset:2560
	v_pk_mul_f32 v[14:15], v[18:19], v[2:3] op_sel_hi:[1,0]
	v_pk_mul_f32 v[16:17], v[20:21], v[2:3] op_sel_hi:[1,0]
	s_waitcnt vmcnt(7)
	v_pk_mul_f32 v[10:11], v[14:15], v[120:121]
	v_pk_mul_f32 v[12:13], v[16:17], v[122:123]
	v_cvt_pk_bf16_f32 v10, v10, v11
	v_cvt_pk_bf16_f32 v11, v12, v13
	global_store_dwordx2 v[50:51], v[10:11], off offset:3072
	s_waitcnt vmcnt(7)
	v_pk_mul_f32 v[6:7], v[6:7], v[124:125]
	v_pk_mul_f32 v[8:9], v[8:9], v[126:127]
	v_cvt_pk_bf16_f32 v6, v6, v7
	v_cvt_pk_bf16_f32 v7, v8, v9
	global_store_dwordx2 v[50:51], v[6:7], off offset:3584
	v_lshl_add_u64 v[50:51], v[50:51], 0, s[18:19]
	s_cbranch_scc1 .LBB0_48
